# v042 + GLA chunk-state delta stored through a per-wave LDS transpose with 16-byte global stores
# baseline (speedup 1.0000x reference)
; #define LAS __attribute__((address_space(3)))
; __device__ __forceinline__ unsigned f2bf(float f) { unsigned u = __float_as_uint(f); return (u + 0x7fffu + ((u >> 16) & 1u)) >> 16; }
; __device__ __forceinline__ int crow(int r, int hi) { return (r & 3) + 8 * (r >> 2) + 4 * hi; }
; #define MFMA32(a, b, c) __builtin_amdgcn_mfma_f32_32x32x16_bf16((a), (b), (c), 0, 0, 0)
; template <int MODE> __device__ __forceinline__ void gla_item(const Args& a, LAS unsigned char* lds, int cid, int h, GlaPre& pf, int next) {
;     ...
;         bf16x8 vf[4];
; #pragma unroll
;         for (int ks = 0; ks < 4; ++ks) vf[ks] = *(const LAS bf16x8*)(VT + (32 * w + l31) * VTS + 16 * ks + 8 * hi);
;         f32x16 acc[4];
; #pragma unroll
;         for (int d = 0; d < 4; ++d) acc[d] = f32x16{};
; #pragma unroll
;         for (int d = 0; d < 4; ++d)
; #pragma unroll
;             for (int ks = 0; ks < 4; ++ks) { const bf16x8 kf = *(const LAS bf16x8*)(KDT + (32 * d + l31) * VTS + 16 * ks + 8 * hi);
;                 acc[d] = prompt ? MFMA32(vf[ks], kf, acc[d]) : MFMA32(kf, vf[ks], acc[d]); }
;         if (prompt) {
;             bf16_t* dst = (bf16_t*)(a.ws + WS_DST) + ((size_t)(cid * 4 + h) * 256 + 32 * w) * 128;
; #pragma unroll
;             for (int d = 0; d < 4; ++d)
; #pragma unroll
;                 for (int r = 0; r < 16; ++r) dst[(size_t)crow(r, hi) * 128 + 32 * d + l31] = (bf16_t)f2bf(acc[d][r]);
.LBB0_463:
	s_or_b64 exec, exec, s[0:1]
	s_ashr_i32 s1, s88, 1
	v_bfe_u32 v71, v20, 5, 1
	v_mov_b32_e32 v2, s1
	v_and_b32_e32 v72, 31, v20
	v_bfi_b32 v2, s86, v2, v20
	v_lshl_add_u32 v6, v71, 4, 0
	v_mad_u64_u32 v[8:9], s[72:73], v2, s77, v[6:7]
	v_mad_u32_u24 v77, v72, s77, v6
	s_waitcnt lgkmcnt(0)
	s_barrier
	ds_read_b128 v[2:5], v8 offset:43008
	ds_read_b128 v[112:115], v8 offset:43040
	ds_read_b128 v[116:119], v8 offset:43072
	ds_read_b128 v[124:127], v8 offset:43104
	ds_read_b128 v[6:9], v77 offset:8192
	ds_read_b128 v[10:13], v77 offset:8224
	s_waitcnt lgkmcnt(1)
	v_mfma_f32_32x32x16_bf16 v[50:65], v[2:5], v[6:9], 0
	ds_read_b128 v[6:9], v77 offset:8256
	ds_read_b128 v[128:131], v77 offset:22048
	s_and_b32 s0, s1, 0xffffffe0
	s_ashr_i32 s1, s0, 31
	v_lshlrev_b64 v[74:75], 16, v[74:75]
	v_lshl_add_u64 v[74:75], s[6:7], 0, v[74:75]
	s_lshl_b64 s[0:1], s[0:1], 8
	s_waitcnt lgkmcnt(2)
	v_mfma_f32_32x32x16_bf16 v[50:65], v[112:115], v[10:13], v[50:65]
	v_lshl_add_u64 v[74:75], v[74:75], 0, s[0:1]
	v_lshlrev_b32_e32 v72, 1, v72
	s_add_u32 s8, s8, 0x20000
	s_addc_u32 s9, s9, 0
	s_addk_i32 s3, 0x1000
	s_add_i32 s53, s53, 0x8000
	s_add_i32 s0, s70, 0xffffff00
	s_waitcnt lgkmcnt(1)
	v_mfma_f32_32x32x16_bf16 v[50:65], v[116:119], v[6:9], v[50:65]
	ds_read_b128 v[6:9], v77 offset:8288
	s_cmpk_gt_i32 s0, 0x2ff
	s_waitcnt lgkmcnt(0)
	v_mfma_f32_32x32x16_bf16 v[50:65], v[124:127], v[6:9], v[50:65]
	ds_read_b128 v[6:9], v77 offset:12800
	s_waitcnt lgkmcnt(0)
	v_mfma_f32_32x32x16_bf16 v[34:49], v[2:5], v[6:9], 0
	ds_read_b128 v[6:9], v77 offset:12832
	s_waitcnt lgkmcnt(0)
	v_mfma_f32_32x32x16_bf16 v[34:49], v[112:115], v[6:9], v[34:49]
	ds_read_b128 v[6:9], v77 offset:12864
	s_waitcnt lgkmcnt(0)
	v_mfma_f32_32x32x16_bf16 v[34:49], v[116:119], v[6:9], v[34:49]
	ds_read_b128 v[6:9], v77 offset:12896
	s_waitcnt lgkmcnt(0)
	v_mfma_f32_32x32x16_bf16 v[34:49], v[124:127], v[6:9], v[34:49]
	ds_read_b128 v[6:9], v77 offset:17408
	s_waitcnt lgkmcnt(0)
	v_mfma_f32_32x32x16_bf16 v[18:33], v[2:5], v[6:9], 0
	ds_read_b128 v[6:9], v77 offset:17440
	s_waitcnt lgkmcnt(0)
	v_mfma_f32_32x32x16_bf16 v[18:33], v[112:115], v[6:9], v[18:33]
	ds_read_b128 v[6:9], v77 offset:17472
	s_waitcnt lgkmcnt(0)
	v_mfma_f32_32x32x16_bf16 v[18:33], v[116:119], v[6:9], v[18:33]
	ds_read_b128 v[6:9], v77 offset:17504
	s_waitcnt lgkmcnt(0)
	v_mfma_f32_32x32x16_bf16 v[18:33], v[124:127], v[6:9], v[18:33]
	ds_read_b128 v[6:9], v77 offset:22016
	s_waitcnt lgkmcnt(0)
	v_mfma_f32_32x32x16_bf16 v[2:17], v[2:5], v[6:9], 0
	v_mfma_f32_32x32x16_bf16 v[2:17], v[112:115], v[128:131], v[2:17]
	ds_read_b128 v[112:115], v77 offset:22080
	s_waitcnt lgkmcnt(0)
	v_mfma_f32_32x32x16_bf16 v[2:17], v[116:119], v[112:115], v[2:17]
	ds_read_b128 v[112:115], v77 offset:22112
	s_waitcnt lgkmcnt(0)
	v_mfma_f32_32x32x16_bf16 v[2:17], v[124:127], v[112:115], v[2:17]
	v_lshlrev_b32_e32 v200, 12, v1
	v_add_u32_e32 v200, 0x16000, v200
	v_lshl_add_u32 v201, v71, 9, v200
	v_add_u32_e32 v201, v201, v72
	v_mbcnt_lo_u32_b32 v202, -1, 0
	v_mbcnt_hi_u32_b32 v202, -1, v202
	v_lshrrev_b32_e32 v203, 3, v202
	v_and_b32_e32 v204, 7, v202
	v_lshlrev_b32_e32 v205, 7, v203
	v_lshl_add_u32 v205, v204, 4, v205
	v_add_u32_e32 v205, v200, v205
	v_lshlrev_b32_e32 v206, 8, v203
	v_lshl_add_u32 v206, v204, 4, v206
	v_mov_b32_e32 v207, 0
	v_lshl_add_u64 v[208:209], v[74:75], 0, v[206:207]
	v_add_co_u32_e32 v210, vcc, 0x1000, v208
	s_nop 1
	v_addc_co_u32_e32 v211, vcc, 0, v209, vcc
	v_cvt_pk_bf16_f32 v212, v50, v50
	ds_write_b16 v201, v212
	v_cvt_pk_bf16_f32 v213, v51, v51
	ds_write_b16 v201, v213 offset:128
	v_cvt_pk_bf16_f32 v214, v52, v52
	ds_write_b16 v201, v214 offset:256
	v_cvt_pk_bf16_f32 v215, v53, v53
	ds_write_b16 v201, v215 offset:384
	v_cvt_pk_bf16_f32 v212, v54, v54
	ds_write_b16 v201, v212 offset:1024
	v_cvt_pk_bf16_f32 v213, v55, v55
	ds_write_b16 v201, v213 offset:1152
	v_cvt_pk_bf16_f32 v214, v56, v56
	ds_write_b16 v201, v214 offset:1280
	v_cvt_pk_bf16_f32 v215, v57, v57
	ds_write_b16 v201, v215 offset:1408
	v_cvt_pk_bf16_f32 v212, v58, v58
	ds_write_b16 v201, v212 offset:2048
	v_cvt_pk_bf16_f32 v213, v59, v59
	ds_write_b16 v201, v213 offset:2176
	v_cvt_pk_bf16_f32 v214, v60, v60
	ds_write_b16 v201, v214 offset:2304
	v_cvt_pk_bf16_f32 v215, v61, v61
	ds_write_b16 v201, v215 offset:2432
	v_cvt_pk_bf16_f32 v212, v62, v62
	ds_write_b16 v201, v212 offset:3072
	v_cvt_pk_bf16_f32 v213, v63, v63
	ds_write_b16 v201, v213 offset:3200
	v_cvt_pk_bf16_f32 v214, v64, v64
	ds_write_b16 v201, v214 offset:3328
	v_cvt_pk_bf16_f32 v215, v65, v65
	ds_write_b16 v201, v215 offset:3456
	v_cvt_pk_bf16_f32 v212, v34, v34
	ds_write_b16 v201, v212 offset:64
	v_cvt_pk_bf16_f32 v213, v35, v35
	ds_write_b16 v201, v213 offset:192
	v_cvt_pk_bf16_f32 v214, v36, v36
	ds_write_b16 v201, v214 offset:320
	v_cvt_pk_bf16_f32 v215, v37, v37
	ds_write_b16 v201, v215 offset:448
	v_cvt_pk_bf16_f32 v212, v38, v38
	ds_write_b16 v201, v212 offset:1088
	v_cvt_pk_bf16_f32 v213, v39, v39
	ds_write_b16 v201, v213 offset:1216
	v_cvt_pk_bf16_f32 v214, v40, v40
	ds_write_b16 v201, v214 offset:1344
	v_cvt_pk_bf16_f32 v215, v41, v41
	ds_write_b16 v201, v215 offset:1472
	v_cvt_pk_bf16_f32 v212, v42, v42
	ds_write_b16 v201, v212 offset:2112
	v_cvt_pk_bf16_f32 v213, v43, v43
	ds_write_b16 v201, v213 offset:2240
	v_cvt_pk_bf16_f32 v214, v44, v44
	ds_write_b16 v201, v214 offset:2368
	v_cvt_pk_bf16_f32 v215, v45, v45
	ds_write_b16 v201, v215 offset:2496
	v_cvt_pk_bf16_f32 v212, v46, v46
	ds_write_b16 v201, v212 offset:3136
	v_cvt_pk_bf16_f32 v213, v47, v47
	ds_write_b16 v201, v213 offset:3264
	v_cvt_pk_bf16_f32 v214, v48, v48
	ds_write_b16 v201, v214 offset:3392
	v_cvt_pk_bf16_f32 v215, v49, v49
	ds_write_b16 v201, v215 offset:3520
	s_waitcnt lgkmcnt(0)
; __device__ __forceinline__ unsigned f2bf(float f) { unsigned u = __float_as_uint(f); return (u + 0x7fffu + ((u >> 16) & 1u)) >> 16; }
; __device__ __forceinline__ int crow(int r, int hi) { return (r & 3) + 8 * (r >> 2) + 4 * hi; }
; template <int MODE> __device__ __forceinline__ void gla_item(const Args& a, LAS unsigned char* lds, int cid, int h, GlaPre& pf, int next) {
;     ...
;         if (prompt) {
;             bf16_t* dst = (bf16_t*)(a.ws + WS_DST) + ((size_t)(cid * 4 + h) * 256 + 32 * w) * 128;
; #pragma unroll
;             for (int d = 0; d < 4; ++d)
; #pragma unroll
;                 for (int r = 0; r < 16; ++r) dst[(size_t)crow(r, hi) * 128 + 32 * d + l31] = (bf16_t)f2bf(acc[d][r]);
;     ...
;     __syncthreads();
	ds_read_b128 v[216:219], v205
	ds_read_b128 v[220:223], v205 offset:1024
	ds_read_b128 v[224:227], v205 offset:2048
	ds_read_b128 v[228:231], v205 offset:3072
	s_waitcnt lgkmcnt(0)
	global_store_dwordx4 v[208:209], v[216:219], off
	global_store_dwordx4 v[208:209], v[220:223], off offset:2048
	global_store_dwordx4 v[210:211], v[224:227], off
	global_store_dwordx4 v[210:211], v[228:231], off offset:2048
	s_nop 1
	v_cvt_pk_bf16_f32 v212, v18, v18
	ds_write_b16 v201, v212
	v_cvt_pk_bf16_f32 v213, v19, v19
	ds_write_b16 v201, v213 offset:128
	v_cvt_pk_bf16_f32 v214, v20, v20
	ds_write_b16 v201, v214 offset:256
	v_cvt_pk_bf16_f32 v215, v21, v21
	ds_write_b16 v201, v215 offset:384
	v_cvt_pk_bf16_f32 v212, v22, v22
	ds_write_b16 v201, v212 offset:1024
	v_cvt_pk_bf16_f32 v213, v23, v23
	ds_write_b16 v201, v213 offset:1152
	v_cvt_pk_bf16_f32 v214, v24, v24
	ds_write_b16 v201, v214 offset:1280
	v_cvt_pk_bf16_f32 v215, v25, v25
	ds_write_b16 v201, v215 offset:1408
	v_cvt_pk_bf16_f32 v212, v26, v26
	ds_write_b16 v201, v212 offset:2048
	v_cvt_pk_bf16_f32 v213, v27, v27
	ds_write_b16 v201, v213 offset:2176
	v_cvt_pk_bf16_f32 v214, v28, v28
	ds_write_b16 v201, v214 offset:2304
	v_cvt_pk_bf16_f32 v215, v29, v29
	ds_write_b16 v201, v215 offset:2432
	v_cvt_pk_bf16_f32 v212, v30, v30
	ds_write_b16 v201, v212 offset:3072
	v_cvt_pk_bf16_f32 v213, v31, v31
	ds_write_b16 v201, v213 offset:3200
	v_cvt_pk_bf16_f32 v214, v32, v32
	ds_write_b16 v201, v214 offset:3328
	v_cvt_pk_bf16_f32 v215, v33, v33
	ds_write_b16 v201, v215 offset:3456
	v_cvt_pk_bf16_f32 v212, v2, v2
	ds_write_b16 v201, v212 offset:64
	v_cvt_pk_bf16_f32 v213, v3, v3
	ds_write_b16 v201, v213 offset:192
	v_cvt_pk_bf16_f32 v214, v4, v4
	ds_write_b16 v201, v214 offset:320
	v_cvt_pk_bf16_f32 v215, v5, v5
	ds_write_b16 v201, v215 offset:448
	v_cvt_pk_bf16_f32 v212, v6, v6
	ds_write_b16 v201, v212 offset:1088
	v_cvt_pk_bf16_f32 v213, v7, v7
	ds_write_b16 v201, v213 offset:1216
	v_cvt_pk_bf16_f32 v214, v8, v8
	ds_write_b16 v201, v214 offset:1344
	v_cvt_pk_bf16_f32 v215, v9, v9
	ds_write_b16 v201, v215 offset:1472
	v_cvt_pk_bf16_f32 v212, v10, v10
	ds_write_b16 v201, v212 offset:2112
	v_cvt_pk_bf16_f32 v213, v11, v11
	ds_write_b16 v201, v213 offset:2240
	v_cvt_pk_bf16_f32 v214, v12, v12
	ds_write_b16 v201, v214 offset:2368
	v_cvt_pk_bf16_f32 v215, v13, v13
	ds_write_b16 v201, v215 offset:2496
	v_cvt_pk_bf16_f32 v212, v14, v14
	ds_write_b16 v201, v212 offset:3136
	v_cvt_pk_bf16_f32 v213, v15, v15
	ds_write_b16 v201, v213 offset:3264
	v_cvt_pk_bf16_f32 v214, v16, v16
	ds_write_b16 v201, v214 offset:3392
	v_cvt_pk_bf16_f32 v215, v17, v17
	ds_write_b16 v201, v215 offset:3520
	s_waitcnt lgkmcnt(0)
	ds_read_b128 v[216:219], v205
	ds_read_b128 v[220:223], v205 offset:1024
	ds_read_b128 v[224:227], v205 offset:2048
	ds_read_b128 v[228:231], v205 offset:3072
	s_waitcnt lgkmcnt(0)
	global_store_dwordx4 v[208:209], v[216:219], off offset:128
	global_store_dwordx4 v[208:209], v[220:223], off offset:2176
	global_store_dwordx4 v[210:211], v[224:227], off offset:128
	global_store_dwordx4 v[210:211], v[228:231], off offset:2176
	s_nop 1
	s_waitcnt vmcnt(63) expcnt(7) lgkmcnt(15)
	s_barrier
	s_cbranch_scc1 .LBB0_465
	s_mov_b64 s[72:73], s[70:71]
	s_branch .LBB0_457
